# nt streaming hint on the final phase's 32 output stores (written once, never re-read), on top of the P0+P1 nt input loads
# speedup vs baseline: 1.0193x; 1.0088x over previous
; #define PG8_LAS __attribute__((address_space(3)))
; __device__ __forceinline__ unsigned cvt_pk_bf16(float lo, float hi) { f32x2c_t v = {lo, hi}; bf16x2c_t b = __builtin_convertvector(v, bf16x2c_t); return __builtin_bit_cast(unsigned, b); }
;     __device__ __forceinline__ void fused(f32x4 (&acc)[2][2][4][2], const Unit& u, int wr, int wc, int fr, int fq, PG8_LAS unsigned char* lds, int wid, int lane) const {
;     ...
;         const float qnan = __builtin_nanf("");
; #pragma unroll
;         for (int bj = 0; bj < 2; ++bj)
; #pragma unroll
;             for (int n = 0; n < 2; ++n) { const int c = col0 + bj * HALF + n * 16; const f32x4 g4 = *(const f32x4*)(gam + c), b4 = *(const f32x4*)(bet + c);
; #pragma unroll
;                 for (int ai = 0; ai < 2; ++ai)
; #pragma unroll
;                     for (int m = 0; m < 4; ++m) { const int r = ai * HALF + wr * 64 + m * 16 + fr; const f32x2v sr = S[r]; const size_t o = (size_t)(u.pm * BM + r) * ldc + c;
;                         f32x4 v = (acc[ai][bj][m][n] - sr.x) * sr.y * g4 + b4; if (bad) v = (f32x4){qnan, qnan, qnan, qnan};
;                         if (OUT_BF16) { u32x2v w; w.x = cvt_pk_bf16(v[0], v[1]); w.y = cvt_pk_bf16(v[2], v[3]); *(PG8_LAS u32x2v*)(lds + 16384 + r * 528 + (c - u.pn * BM) * 2) = w; }
;                         else *(f32x4*)((float*)out + o) = v; } }
.LBB0_919:
	s_or_b64 exec, exec, s[2:3]
	v_lshlrev_b64 v[158:159], 2, v[128:129]
	s_waitcnt lgkmcnt(0)
	s_barrier
	v_lshl_add_u64 v[148:149], s[62:63], 0, v[158:159]
	v_lshl_add_u64 v[150:151], s[64:65], 0, v[158:159]
	global_load_dwordx4 v[140:143], v[148:149], off
	global_load_dwordx4 v[144:147], v[150:151], off
	v_lshl_add_u32 v128, v152, 3, 0
	v_add_u32_e32 v170, 0x2000, v128
	ds_read2_b64 v[136:139], v170 offset1:16
	ds_read2_b64 v[132:135], v170 offset0:32 offset1:48
	ds_read2_b64 v[128:131], v170 offset0:128 offset1:144
	v_add_u32_e32 v160, s16, v152
	v_ashrrev_i32_e32 v161, 31, v160
	v_add_u32_e32 v152, 16, v160
	v_add_u32_e32 v154, 32, v160
	s_waitcnt lgkmcnt(2)
	v_sub_f32_e32 v107, v107, v136
	v_sub_f32_e32 v106, v106, v136
	v_sub_f32_e32 v105, v105, v136
	v_sub_f32_e32 v104, v104, v136
	v_add_u32_e32 v156, 48, v160
	v_lshlrev_b64 v[164:165], 12, v[160:161]
	v_ashrrev_i32_e32 v153, 31, v152
	v_ashrrev_i32_e32 v155, 31, v154
	v_sub_f32_e32 v119, v119, v138
	v_sub_f32_e32 v118, v118, v138
	v_sub_f32_e32 v117, v117, v138
	v_sub_f32_e32 v116, v116, v138
	s_waitcnt lgkmcnt(1)
	v_sub_f32_e32 v127, v127, v132
	v_sub_f32_e32 v126, v126, v132
	v_sub_f32_e32 v125, v125, v132
	v_sub_f32_e32 v124, v124, v132
	v_pk_mul_f32 v[104:105], v[136:137], v[104:105] op_sel:[1,0]
	v_pk_mul_f32 v[106:107], v[136:137], v[106:107] op_sel:[1,0]
	v_mov_b32_e32 v162, 0x7fc00000
	v_ashrrev_i32_e32 v157, 31, v156
	v_lshl_add_u64 v[164:165], s[66:67], 0, v[164:165]
	v_lshlrev_b64 v[152:153], 12, v[152:153]
	v_lshlrev_b64 v[154:155], 12, v[154:155]
	v_sub_f32_e32 v123, v123, v134
	v_sub_f32_e32 v122, v122, v134
	v_sub_f32_e32 v121, v121, v134
	v_sub_f32_e32 v120, v120, v134
	v_pk_mul_f32 v[116:117], v[138:139], v[116:117] op_sel:[1,0]
	v_pk_mul_f32 v[118:119], v[138:139], v[118:119] op_sel:[1,0]
	v_pk_mul_f32 v[124:125], v[132:133], v[124:125] op_sel:[1,0]
	v_pk_mul_f32 v[126:127], v[132:133], v[126:127] op_sel:[1,0]
	v_cmp_eq_u32_e32 vcc, 0, v163
	v_lshlrev_b64 v[166:167], 12, v[156:157]
	v_lshl_add_u64 v[156:157], v[164:165], 0, v[158:159]
	v_lshl_add_u64 v[152:153], s[66:67], 0, v[152:153]
	v_lshl_add_u64 v[164:165], s[66:67], 0, v[154:155]
	v_pk_mul_f32 v[120:121], v[134:135], v[120:121] op_sel:[1,0]
	v_pk_mul_f32 v[122:123], v[134:135], v[122:123] op_sel:[1,0]
	s_waitcnt lgkmcnt(0)
	v_sub_f32_e32 v101, v101, v128
	v_sub_f32_e32 v100, v100, v128
	v_lshl_add_u64 v[154:155], v[152:153], 0, v[158:159]
	v_lshl_add_u64 v[152:153], v[164:165], 0, v[158:159]
	v_sub_f32_e32 v103, v103, v128
	v_sub_f32_e32 v102, v102, v128
	v_pk_mul_f32 v[100:101], v[128:129], v[100:101] op_sel:[1,0]
	v_pk_mul_f32 v[102:103], v[128:129], v[102:103] op_sel:[1,0]
	v_sub_f32_e32 v69, v69, v130
	v_sub_f32_e32 v68, v68, v130
	v_sub_f32_e32 v71, v71, v130
	v_sub_f32_e32 v70, v70, v130
	v_pk_mul_f32 v[68:69], v[130:131], v[68:69] op_sel:[1,0]
	v_pk_mul_f32 v[70:71], v[130:131], v[70:71] op_sel:[1,0]
	v_lshl_add_u64 v[166:167], s[66:67], 0, v[166:167]
	v_sub_f32_e32 v17, v17, v136
	v_sub_f32_e32 v16, v16, v136
	v_pk_mul_f32 v[16:17], v[136:137], v[16:17] op_sel:[1,0]
	s_waitcnt vmcnt(0)
	v_pk_fma_f32 v[106:107], v[142:143], v[106:107], v[146:147]
	v_pk_fma_f32 v[104:105], v[140:141], v[104:105], v[144:145]
	v_pk_fma_f32 v[118:119], v[142:143], v[118:119], v[146:147]
	v_pk_fma_f32 v[116:117], v[140:141], v[116:117], v[144:145]
	v_pk_fma_f32 v[126:127], v[142:143], v[126:127], v[146:147]
	v_pk_fma_f32 v[124:125], v[140:141], v[124:125], v[144:145]
	v_cndmask_b32_e32 v107, v162, v107, vcc
	v_cndmask_b32_e32 v106, v162, v106, vcc
	v_cndmask_b32_e32 v105, v162, v105, vcc
	v_cndmask_b32_e32 v104, v162, v104, vcc
	v_pk_fma_f32 v[164:165], v[142:143], v[122:123], v[146:147]
	v_pk_fma_f32 v[168:169], v[140:141], v[120:121], v[144:145]
	v_cndmask_b32_e32 v119, v162, v119, vcc
	v_cndmask_b32_e32 v118, v162, v118, vcc
	v_cndmask_b32_e32 v117, v162, v117, vcc
	v_cndmask_b32_e32 v116, v162, v116, vcc
	v_cndmask_b32_e32 v123, v162, v127, vcc
	v_cndmask_b32_e32 v122, v162, v126, vcc
	v_cndmask_b32_e32 v121, v162, v125, vcc
	v_cndmask_b32_e32 v120, v162, v124, vcc
	global_store_dwordx4 v[156:157], v[104:107], off nt
	global_store_dwordx4 v[154:155], v[116:119], off nt
	global_store_dwordx4 v[152:153], v[120:123], off nt
	v_add_u32_e32 v106, 0x80, v160
	v_ashrrev_i32_e32 v107, 31, v106
	v_pk_fma_f32 v[100:101], v[140:141], v[100:101], v[144:145]
	v_pk_fma_f32 v[102:103], v[142:143], v[102:103], v[146:147]
	v_cndmask_b32_e32 v117, v162, v101, vcc
	v_cndmask_b32_e32 v116, v162, v100, vcc
	v_lshlrev_b64 v[100:101], 12, v[106:107]
	v_cndmask_b32_e32 v118, v162, v102, vcc
	v_lshl_add_u64 v[100:101], s[66:67], 0, v[100:101]
	v_add_u32_e32 v102, 0x90, v160
	v_cndmask_b32_e32 v119, v162, v103, vcc
	v_lshl_add_u64 v[100:101], v[100:101], 0, v[158:159]
	v_ashrrev_i32_e32 v103, 31, v102
	v_pk_fma_f32 v[68:69], v[140:141], v[68:69], v[144:145]
	global_store_dwordx4 v[100:101], v[116:119], off nt
	v_pk_fma_f32 v[70:71], v[142:143], v[70:71], v[146:147]
	v_add_u32_e32 v106, 0xa0, v160
	v_cndmask_b32_e32 v117, v162, v69, vcc
	v_cndmask_b32_e32 v116, v162, v68, vcc
	v_lshlrev_b64 v[68:69], 12, v[102:103]
	v_cndmask_b32_e32 v119, v162, v71, vcc
	v_cndmask_b32_e32 v118, v162, v70, vcc
	v_lshl_add_u64 v[102:103], s[66:67], 0, v[68:69]
	ds_read2_b64 v[68:71], v170 offset0:160 offset1:176
	v_lshl_add_u64 v[102:103], v[102:103], 0, v[158:159]
	v_ashrrev_i32_e32 v107, 31, v106
	global_store_dwordx4 v[102:103], v[116:119], off nt
	v_cndmask_b32_e32 v127, v162, v165, vcc
	s_waitcnt lgkmcnt(0)
; #define PG8_LAS __attribute__((address_space(3)))
; __device__ __forceinline__ unsigned cvt_pk_bf16(float lo, float hi) { f32x2c_t v = {lo, hi}; bf16x2c_t b = __builtin_convertvector(v, bf16x2c_t); return __builtin_bit_cast(unsigned, b); }
;     __device__ __forceinline__ void fused(f32x4 (&acc)[2][2][4][2], const Unit& u, int wr, int wc, int fr, int fq, PG8_LAS unsigned char* lds, int wid, int lane) const {
;     ...
;             for (int n = 0; n < 2; ++n) { const int c = col0 + bj * HALF + n * 16; const f32x4 g4 = *(const f32x4*)(gam + c), b4 = *(const f32x4*)(bet + c);
; #pragma unroll
;                 for (int ai = 0; ai < 2; ++ai)
; #pragma unroll
;                     for (int m = 0; m < 4; ++m) { const int r = ai * HALF + wr * 64 + m * 16 + fr; const f32x2v sr = S[r]; const size_t o = (size_t)(u.pm * BM + r) * ldc + c;
;                         f32x4 v = (acc[ai][bj][m][n] - sr.x) * sr.y * g4 + b4; if (bad) v = (f32x4){qnan, qnan, qnan, qnan};
;                         if (OUT_BF16) { u32x2v w; w.x = cvt_pk_bf16(v[0], v[1]); w.y = cvt_pk_bf16(v[2], v[3]); *(PG8_LAS u32x2v*)(lds + 16384 + r * 528 + (c - u.pn * BM) * 2) = w; }
;                         else *(f32x4*)((float*)out + o) = v; } }
	v_sub_f32_e32 v37, v37, v68
	v_sub_f32_e32 v36, v36, v68
	v_sub_f32_e32 v39, v39, v68
	v_sub_f32_e32 v38, v38, v68
	v_pk_mul_f32 v[36:37], v[68:69], v[36:37] op_sel:[1,0]
	v_pk_mul_f32 v[38:39], v[68:69], v[38:39] op_sel:[1,0]
	v_pk_fma_f32 v[36:37], v[140:141], v[36:37], v[144:145]
	v_pk_fma_f32 v[38:39], v[142:143], v[38:39], v[146:147]
	v_cndmask_b32_e32 v117, v162, v37, vcc
	v_cndmask_b32_e32 v116, v162, v36, vcc
	v_lshlrev_b64 v[36:37], 12, v[106:107]
	v_sub_f32_e32 v13, v13, v70
	v_sub_f32_e32 v12, v12, v70
	v_cndmask_b32_e32 v118, v162, v38, vcc
	v_lshl_add_u64 v[36:37], s[66:67], 0, v[36:37]
	v_add_u32_e32 v38, 0xb0, v160
	v_pk_mul_f32 v[12:13], v[70:71], v[12:13] op_sel:[1,0]
	v_cndmask_b32_e32 v119, v162, v39, vcc
	v_lshl_add_u64 v[36:37], v[36:37], 0, v[158:159]
	v_ashrrev_i32_e32 v39, 31, v38
	v_sub_f32_e32 v15, v15, v70
	v_sub_f32_e32 v14, v14, v70
	v_pk_fma_f32 v[12:13], v[140:141], v[12:13], v[144:145]
	global_store_dwordx4 v[36:37], v[116:119], off nt
	v_pk_mul_f32 v[14:15], v[70:71], v[14:15] op_sel:[1,0]
	v_cndmask_b32_e32 v126, v162, v164, vcc
	v_cndmask_b32_e32 v117, v162, v13, vcc
	v_cndmask_b32_e32 v116, v162, v12, vcc
	v_lshlrev_b64 v[12:13], 12, v[38:39]
	v_pk_fma_f32 v[14:15], v[142:143], v[14:15], v[146:147]
	v_lshl_add_u64 v[12:13], s[66:67], 0, v[12:13]
	v_cndmask_b32_e32 v125, v162, v169, vcc
	v_cndmask_b32_e32 v124, v162, v168, vcc
	v_lshl_add_u64 v[104:105], v[166:167], 0, v[158:159]
	v_cndmask_b32_e32 v119, v162, v15, vcc
	v_cndmask_b32_e32 v118, v162, v14, vcc
	v_lshl_add_u64 v[12:13], v[12:13], 0, v[158:159]
	global_store_dwordx4 v[104:105], v[124:127], off nt
	global_store_dwordx4 v[12:13], v[116:119], off nt
	global_load_dwordx4 v[116:119], v[148:149], off offset:64
	s_nop 0
	global_load_dwordx4 v[120:123], v[150:151], off offset:64
	v_sub_f32_e32 v15, v75, v136
	v_sub_f32_e32 v14, v74, v136
	v_pk_mul_f32 v[14:15], v[136:137], v[14:15] op_sel:[1,0]
	v_sub_f32_e32 v39, v73, v136
	v_sub_f32_e32 v38, v72, v136
	v_pk_mul_f32 v[38:39], v[136:137], v[38:39] op_sel:[1,0]
	v_sub_f32_e32 v29, v29, v68
	v_sub_f32_e32 v28, v28, v68
	v_sub_f32_e32 v11, v11, v70
	v_sub_f32_e32 v10, v10, v70
	v_sub_f32_e32 v9, v9, v70
	v_sub_f32_e32 v8, v8, v70
	v_pk_mul_f32 v[28:29], v[68:69], v[28:29] op_sel:[1,0]
	v_pk_mul_f32 v[8:9], v[70:71], v[8:9] op_sel:[1,0]
	v_pk_mul_f32 v[10:11], v[70:71], v[10:11] op_sel:[1,0]
	v_sub_f32_e32 v25, v25, v68
	v_sub_f32_e32 v24, v24, v68
	v_sub_f32_e32 v7, v7, v70
	v_sub_f32_e32 v6, v6, v70
	v_sub_f32_e32 v5, v5, v70
	v_sub_f32_e32 v4, v4, v70
	v_pk_mul_f32 v[24:25], v[68:69], v[24:25] op_sel:[1,0]
	v_pk_mul_f32 v[4:5], v[70:71], v[4:5] op_sel:[1,0]
	v_pk_mul_f32 v[6:7], v[70:71], v[6:7] op_sel:[1,0]
	v_sub_f32_e32 v3, v3, v70
	v_sub_f32_e32 v2, v2, v70
	v_sub_f32_e32 v1, v1, v70
	v_sub_f32_e32 v0, v0, v70
	v_pk_mul_f32 v[0:1], v[70:71], v[0:1] op_sel:[1,0]
	v_pk_mul_f32 v[2:3], v[70:71], v[2:3] op_sel:[1,0]
	s_waitcnt vmcnt(0)
	v_pk_fma_f32 v[14:15], v[14:15], v[118:119], v[122:123]
	s_nop 0
	v_cndmask_b32_e32 v75, v162, v15, vcc
	v_cndmask_b32_e32 v74, v162, v14, vcc
	v_sub_f32_e32 v15, v91, v138
	v_sub_f32_e32 v14, v90, v138
	v_pk_fma_f32 v[38:39], v[38:39], v[116:117], v[120:121]
	v_pk_mul_f32 v[14:15], v[138:139], v[14:15] op_sel:[1,0]
	v_cndmask_b32_e32 v73, v162, v39, vcc
	v_cndmask_b32_e32 v72, v162, v38, vcc
	v_sub_f32_e32 v39, v89, v138
	v_sub_f32_e32 v38, v88, v138
	v_pk_fma_f32 v[14:15], v[14:15], v[118:119], v[122:123]
	global_store_dwordx4 v[156:157], v[72:75], off offset:64 nt
	v_pk_mul_f32 v[38:39], v[138:139], v[38:39] op_sel:[1,0]
	v_pk_fma_f32 v[28:29], v[28:29], v[116:117], v[120:121]
	v_cndmask_b32_e32 v75, v162, v15, vcc
	v_cndmask_b32_e32 v74, v162, v14, vcc
	v_sub_f32_e32 v15, v111, v132
	v_sub_f32_e32 v14, v110, v132
	v_pk_fma_f32 v[38:39], v[38:39], v[116:117], v[120:121]
	v_pk_mul_f32 v[14:15], v[132:133], v[14:15] op_sel:[1,0]
	v_cndmask_b32_e32 v73, v162, v39, vcc
	v_cndmask_b32_e32 v72, v162, v38, vcc
	v_sub_f32_e32 v39, v109, v132
	v_sub_f32_e32 v38, v108, v132
	v_pk_fma_f32 v[14:15], v[14:15], v[118:119], v[122:123]
	global_store_dwordx4 v[154:155], v[72:75], off offset:64 nt
	v_pk_mul_f32 v[38:39], v[132:133], v[38:39] op_sel:[1,0]
	v_pk_fma_f32 v[10:11], v[118:119], v[10:11], v[122:123]
	v_cndmask_b32_e32 v75, v162, v15, vcc
	v_cndmask_b32_e32 v74, v162, v14, vcc
	v_sub_f32_e32 v15, v115, v134
	v_sub_f32_e32 v14, v114, v134
	v_pk_fma_f32 v[38:39], v[38:39], v[116:117], v[120:121]
	v_pk_mul_f32 v[14:15], v[134:135], v[14:15] op_sel:[1,0]
	v_cndmask_b32_e32 v73, v162, v39, vcc
	v_cndmask_b32_e32 v72, v162, v38, vcc
	v_sub_f32_e32 v39, v113, v134
	v_sub_f32_e32 v38, v112, v134
	v_pk_fma_f32 v[14:15], v[14:15], v[118:119], v[122:123]
	global_store_dwordx4 v[152:153], v[72:75], off offset:64 nt
	v_pk_mul_f32 v[38:39], v[134:135], v[38:39] op_sel:[1,0]
	v_pk_fma_f32 v[8:9], v[116:117], v[8:9], v[120:121]
	v_cndmask_b32_e32 v75, v162, v15, vcc
	v_cndmask_b32_e32 v74, v162, v14, vcc
	v_sub_f32_e32 v15, v99, v128
	v_sub_f32_e32 v14, v98, v128
	v_pk_fma_f32 v[38:39], v[38:39], v[116:117], v[120:121]
	v_pk_mul_f32 v[14:15], v[128:129], v[14:15] op_sel:[1,0]
	v_cndmask_b32_e32 v73, v162, v39, vcc
	v_cndmask_b32_e32 v72, v162, v38, vcc
	v_pk_fma_f32 v[14:15], v[14:15], v[118:119], v[122:123]
	global_store_dwordx4 v[104:105], v[72:75], off offset:64 nt
	v_sub_f32_e32 v39, v97, v128
	v_sub_f32_e32 v38, v96, v128
	v_cndmask_b32_e32 v75, v162, v15, vcc
	v_cndmask_b32_e32 v74, v162, v14, vcc
	v_sub_f32_e32 v15, v67, v130
	v_sub_f32_e32 v14, v66, v130
	v_pk_mul_f32 v[38:39], v[128:129], v[38:39] op_sel:[1,0]
	v_pk_mul_f32 v[14:15], v[130:131], v[14:15] op_sel:[1,0]
; #define PG8_LAS __attribute__((address_space(3)))
; __device__ __forceinline__ unsigned cvt_pk_bf16(float lo, float hi) { f32x2c_t v = {lo, hi}; bf16x2c_t b = __builtin_convertvector(v, bf16x2c_t); return __builtin_bit_cast(unsigned, b); }
;     __device__ __forceinline__ void fused(f32x4 (&acc)[2][2][4][2], const Unit& u, int wr, int wc, int fr, int fq, PG8_LAS unsigned char* lds, int wid, int lane) const {
;     ...
;             for (int n = 0; n < 2; ++n) { const int c = col0 + bj * HALF + n * 16; const f32x4 g4 = *(const f32x4*)(gam + c), b4 = *(const f32x4*)(bet + c);
; #pragma unroll
;                 for (int ai = 0; ai < 2; ++ai)
; #pragma unroll
;                     for (int m = 0; m < 4; ++m) { const int r = ai * HALF + wr * 64 + m * 16 + fr; const f32x2v sr = S[r]; const size_t o = (size_t)(u.pm * BM + r) * ldc + c;
;                         f32x4 v = (acc[ai][bj][m][n] - sr.x) * sr.y * g4 + b4; if (bad) v = (f32x4){qnan, qnan, qnan, qnan};
;                         if (OUT_BF16) { u32x2v w; w.x = cvt_pk_bf16(v[0], v[1]); w.y = cvt_pk_bf16(v[2], v[3]); *(PG8_LAS u32x2v*)(lds + 16384 + r * 528 + (c - u.pn * BM) * 2) = w; }
;                         else *(f32x4*)((float*)out + o) = v; } }
	v_pk_fma_f32 v[38:39], v[38:39], v[116:117], v[120:121]
	v_pk_fma_f32 v[14:15], v[14:15], v[118:119], v[122:123]
	v_cndmask_b32_e32 v73, v162, v39, vcc
	v_cndmask_b32_e32 v72, v162, v38, vcc
	v_sub_f32_e32 v39, v65, v130
	v_sub_f32_e32 v38, v64, v130
	v_cndmask_b32_e32 v67, v162, v15, vcc
	v_cndmask_b32_e32 v66, v162, v14, vcc
	v_sub_f32_e32 v15, v31, v68
	v_sub_f32_e32 v14, v30, v68
	v_pk_mul_f32 v[38:39], v[130:131], v[38:39] op_sel:[1,0]
	v_pk_mul_f32 v[14:15], v[68:69], v[14:15] op_sel:[1,0]
	v_pk_fma_f32 v[38:39], v[38:39], v[116:117], v[120:121]
	v_pk_fma_f32 v[14:15], v[14:15], v[118:119], v[122:123]
	v_cndmask_b32_e32 v65, v162, v39, vcc
	v_cndmask_b32_e32 v64, v162, v38, vcc
	v_cndmask_b32_e32 v31, v162, v15, vcc
	v_cndmask_b32_e32 v30, v162, v14, vcc
	v_cndmask_b32_e32 v29, v162, v29, vcc
	v_cndmask_b32_e32 v28, v162, v28, vcc
	v_cndmask_b32_e32 v11, v162, v11, vcc
	v_cndmask_b32_e32 v10, v162, v10, vcc
	v_cndmask_b32_e32 v9, v162, v9, vcc
	v_cndmask_b32_e32 v8, v162, v8, vcc
	global_store_dwordx4 v[100:101], v[72:75], off offset:64 nt
	global_store_dwordx4 v[102:103], v[64:67], off offset:64 nt
	global_store_dwordx4 v[36:37], v[28:31], off offset:64 nt
	global_store_dwordx4 v[12:13], v[8:11], off offset:64 nt
	global_load_dwordx4 v[8:11], v[148:149], off offset:512
	s_nop 0
	global_load_dwordx4 v[28:31], v[150:151], off offset:512
	v_sub_f32_e32 v15, v43, v136
	v_sub_f32_e32 v14, v42, v136
	v_sub_f32_e32 v39, v41, v136
	v_sub_f32_e32 v38, v40, v136
	v_pk_mul_f32 v[38:39], v[136:137], v[38:39] op_sel:[1,0]
	v_pk_mul_f32 v[14:15], v[136:137], v[14:15] op_sel:[1,0]
	s_waitcnt vmcnt(0)
	v_pk_fma_f32 v[38:39], v[38:39], v[8:9], v[28:29]
	v_pk_fma_f32 v[14:15], v[14:15], v[10:11], v[30:31]
	v_cndmask_b32_e32 v39, v162, v39, vcc
	v_cndmask_b32_e32 v41, v162, v15, vcc
	v_cndmask_b32_e32 v40, v162, v14, vcc
	v_cndmask_b32_e32 v38, v162, v38, vcc
	global_store_dwordx4 v[156:157], v[38:41], off offset:512 nt
	v_sub_f32_e32 v15, v55, v138
	v_sub_f32_e32 v14, v54, v138
	v_sub_f32_e32 v39, v53, v138
	v_sub_f32_e32 v38, v52, v138
	v_pk_mul_f32 v[38:39], v[138:139], v[38:39] op_sel:[1,0]
	v_pk_mul_f32 v[14:15], v[138:139], v[14:15] op_sel:[1,0]
	v_pk_fma_f32 v[38:39], v[38:39], v[8:9], v[28:29]
	v_pk_fma_f32 v[14:15], v[14:15], v[10:11], v[30:31]
	v_cndmask_b32_e32 v39, v162, v39, vcc
	v_cndmask_b32_e32 v41, v162, v15, vcc
	v_cndmask_b32_e32 v40, v162, v14, vcc
	v_cndmask_b32_e32 v38, v162, v38, vcc
	global_store_dwordx4 v[154:155], v[38:41], off offset:512 nt
	v_sub_f32_e32 v15, v79, v132
	v_sub_f32_e32 v14, v78, v132
	v_sub_f32_e32 v39, v77, v132
	v_sub_f32_e32 v38, v76, v132
	v_pk_mul_f32 v[38:39], v[132:133], v[38:39] op_sel:[1,0]
	v_pk_mul_f32 v[14:15], v[132:133], v[14:15] op_sel:[1,0]
	v_pk_fma_f32 v[38:39], v[38:39], v[8:9], v[28:29]
	v_pk_fma_f32 v[14:15], v[14:15], v[10:11], v[30:31]
	v_cndmask_b32_e32 v39, v162, v39, vcc
	v_cndmask_b32_e32 v41, v162, v15, vcc
	v_cndmask_b32_e32 v40, v162, v14, vcc
	v_cndmask_b32_e32 v38, v162, v38, vcc
	v_sub_f32_e32 v15, v95, v134
	v_sub_f32_e32 v14, v94, v134
	global_store_dwordx4 v[152:153], v[38:41], off offset:512 nt
	v_pk_mul_f32 v[14:15], v[134:135], v[14:15] op_sel:[1,0]
	v_pk_fma_f32 v[24:25], v[24:25], v[8:9], v[28:29]
	v_sub_f32_e32 v39, v93, v134
	v_sub_f32_e32 v38, v92, v134
	v_pk_mul_f32 v[38:39], v[134:135], v[38:39] op_sel:[1,0]
	v_pk_fma_f32 v[14:15], v[14:15], v[10:11], v[30:31]
	v_pk_fma_f32 v[38:39], v[38:39], v[8:9], v[28:29]
	v_cndmask_b32_e32 v41, v162, v15, vcc
	v_cndmask_b32_e32 v40, v162, v14, vcc
	v_sub_f32_e32 v15, v87, v128
	v_sub_f32_e32 v14, v86, v128
	v_cndmask_b32_e32 v39, v162, v39, vcc
	v_cndmask_b32_e32 v38, v162, v38, vcc
	v_pk_mul_f32 v[14:15], v[128:129], v[14:15] op_sel:[1,0]
	global_store_dwordx4 v[104:105], v[38:41], off offset:512 nt
	v_pk_fma_f32 v[14:15], v[14:15], v[10:11], v[30:31]
	v_pk_fma_f32 v[6:7], v[6:7], v[10:11], v[30:31]
	v_sub_f32_e32 v39, v85, v128
	v_sub_f32_e32 v38, v84, v128
	v_pk_mul_f32 v[38:39], v[128:129], v[38:39] op_sel:[1,0]
	v_cndmask_b32_e32 v41, v162, v15, vcc
	v_cndmask_b32_e32 v40, v162, v14, vcc
	v_sub_f32_e32 v15, v59, v130
	v_sub_f32_e32 v14, v58, v130
	v_pk_fma_f32 v[38:39], v[38:39], v[8:9], v[28:29]
	v_pk_mul_f32 v[14:15], v[130:131], v[14:15] op_sel:[1,0]
	v_cndmask_b32_e32 v39, v162, v39, vcc
	v_cndmask_b32_e32 v38, v162, v38, vcc
	v_pk_fma_f32 v[14:15], v[14:15], v[10:11], v[30:31]
	global_store_dwordx4 v[100:101], v[38:41], off offset:512 nt
	v_pk_fma_f32 v[4:5], v[4:5], v[8:9], v[28:29]
	v_cndmask_b32_e32 v25, v162, v25, vcc
	v_sub_f32_e32 v39, v57, v130
	v_sub_f32_e32 v38, v56, v130
	v_cndmask_b32_e32 v41, v162, v15, vcc
	v_cndmask_b32_e32 v40, v162, v14, vcc
	v_sub_f32_e32 v15, v27, v68
	v_sub_f32_e32 v14, v26, v68
	v_pk_mul_f32 v[38:39], v[130:131], v[38:39] op_sel:[1,0]
	v_pk_mul_f32 v[14:15], v[68:69], v[14:15] op_sel:[1,0]
	v_pk_fma_f32 v[38:39], v[38:39], v[8:9], v[28:29]
	v_pk_fma_f32 v[14:15], v[14:15], v[10:11], v[30:31]
	v_cndmask_b32_e32 v39, v162, v39, vcc
	v_cndmask_b32_e32 v38, v162, v38, vcc
	v_cndmask_b32_e32 v27, v162, v15, vcc
	v_cndmask_b32_e32 v26, v162, v14, vcc
	v_cndmask_b32_e32 v24, v162, v24, vcc
	v_cndmask_b32_e32 v7, v162, v7, vcc
	v_cndmask_b32_e32 v6, v162, v6, vcc
	v_cndmask_b32_e32 v5, v162, v5, vcc
	v_cndmask_b32_e32 v4, v162, v4, vcc
	global_store_dwordx4 v[102:103], v[38:41], off offset:512 nt
	global_store_dwordx4 v[36:37], v[24:27], off offset:512 nt
	global_store_dwordx4 v[12:13], v[4:7], off offset:512 nt
	global_load_dwordx4 v[4:7], v[148:149], off offset:576
	s_nop 0
	global_load_dwordx4 v[8:11], v[150:151], off offset:576
	v_sub_f32_e32 v15, v19, v136
	v_sub_f32_e32 v14, v18, v136
	v_pk_mul_f32 v[14:15], v[136:137], v[14:15] op_sel:[1,0]
	s_waitcnt vmcnt(0)
; #define PG8_LAS __attribute__((address_space(3)))
; __device__ __forceinline__ unsigned cvt_pk_bf16(float lo, float hi) { f32x2c_t v = {lo, hi}; bf16x2c_t b = __builtin_convertvector(v, bf16x2c_t); return __builtin_bit_cast(unsigned, b); }
;     __device__ __forceinline__ void fused(f32x4 (&acc)[2][2][4][2], const Unit& u, int wr, int wc, int fr, int fq, PG8_LAS unsigned char* lds, int wid, int lane) const {
;     ...
;             for (int n = 0; n < 2; ++n) { const int c = col0 + bj * HALF + n * 16; const f32x4 g4 = *(const f32x4*)(gam + c), b4 = *(const f32x4*)(bet + c);
; #pragma unroll
;                 for (int ai = 0; ai < 2; ++ai)
; #pragma unroll
;                     for (int m = 0; m < 4; ++m) { const int r = ai * HALF + wr * 64 + m * 16 + fr; const f32x2v sr = S[r]; const size_t o = (size_t)(u.pm * BM + r) * ldc + c;
;                         f32x4 v = (acc[ai][bj][m][n] - sr.x) * sr.y * g4 + b4; if (bad) v = (f32x4){qnan, qnan, qnan, qnan};
;                         if (OUT_BF16) { u32x2v w; w.x = cvt_pk_bf16(v[0], v[1]); w.y = cvt_pk_bf16(v[2], v[3]); *(PG8_LAS u32x2v*)(lds + 16384 + r * 528 + (c - u.pn * BM) * 2) = w; }
;                         else *(f32x4*)((float*)out + o) = v; } }
	v_pk_fma_f32 v[18:19], v[16:17], v[4:5], v[8:9]
	v_pk_fma_f32 v[14:15], v[14:15], v[6:7], v[10:11]
	v_pk_fma_f32 v[2:3], v[2:3], v[6:7], v[10:11]
	v_cndmask_b32_e32 v17, v162, v15, vcc
	v_cndmask_b32_e32 v16, v162, v14, vcc
	v_cndmask_b32_e32 v15, v162, v19, vcc
	v_cndmask_b32_e32 v14, v162, v18, vcc
	global_store_dwordx4 v[156:157], v[14:17], off offset:576 nt
	v_pk_fma_f32 v[0:1], v[0:1], v[4:5], v[8:9]
	v_cndmask_b32_e32 v3, v162, v3, vcc
	v_sub_f32_e32 v15, v35, v138
	v_sub_f32_e32 v14, v34, v138
	v_sub_f32_e32 v17, v33, v138
	v_sub_f32_e32 v16, v32, v138
	v_pk_mul_f32 v[16:17], v[138:139], v[16:17] op_sel:[1,0]
	v_pk_mul_f32 v[14:15], v[138:139], v[14:15] op_sel:[1,0]
	v_pk_fma_f32 v[18:19], v[16:17], v[4:5], v[8:9]
	v_pk_fma_f32 v[14:15], v[14:15], v[6:7], v[10:11]
	v_cndmask_b32_e32 v2, v162, v2, vcc
	v_cndmask_b32_e32 v17, v162, v15, vcc
	v_cndmask_b32_e32 v16, v162, v14, vcc
	v_cndmask_b32_e32 v15, v162, v19, vcc
	v_cndmask_b32_e32 v14, v162, v18, vcc
	global_store_dwordx4 v[154:155], v[14:17], off offset:576 nt
	v_cndmask_b32_e32 v1, v162, v1, vcc
	v_cndmask_b32_e32 v0, v162, v0, vcc
	v_sub_f32_e32 v15, v47, v132
	v_sub_f32_e32 v14, v46, v132
	v_sub_f32_e32 v17, v45, v132
	v_sub_f32_e32 v16, v44, v132
	v_pk_mul_f32 v[16:17], v[132:133], v[16:17] op_sel:[1,0]
	v_pk_mul_f32 v[14:15], v[132:133], v[14:15] op_sel:[1,0]
	v_pk_fma_f32 v[18:19], v[16:17], v[4:5], v[8:9]
	v_pk_fma_f32 v[14:15], v[14:15], v[6:7], v[10:11]
	s_nop 0
	v_cndmask_b32_e32 v17, v162, v15, vcc
	v_cndmask_b32_e32 v16, v162, v14, vcc
	v_cndmask_b32_e32 v15, v162, v19, vcc
	v_cndmask_b32_e32 v14, v162, v18, vcc
	global_store_dwordx4 v[152:153], v[14:17], off offset:576 nt
	s_nop 1
	v_sub_f32_e32 v15, v63, v134
	v_sub_f32_e32 v14, v62, v134
	v_sub_f32_e32 v17, v61, v134
	v_sub_f32_e32 v16, v60, v134
	v_pk_mul_f32 v[16:17], v[134:135], v[16:17] op_sel:[1,0]
	v_pk_mul_f32 v[14:15], v[134:135], v[14:15] op_sel:[1,0]
	v_pk_fma_f32 v[18:19], v[16:17], v[4:5], v[8:9]
	v_pk_fma_f32 v[14:15], v[14:15], v[6:7], v[10:11]
	s_nop 0
	v_cndmask_b32_e32 v17, v162, v15, vcc
	v_cndmask_b32_e32 v16, v162, v14, vcc
	v_cndmask_b32_e32 v15, v162, v19, vcc
	v_cndmask_b32_e32 v14, v162, v18, vcc
	global_store_dwordx4 v[104:105], v[14:17], off offset:576 nt
	global_store_dwordx4 v[12:13], v[0:3], off offset:576 nt
	s_nop 0
	v_sub_f32_e32 v15, v83, v128
	v_sub_f32_e32 v14, v82, v128
	v_sub_f32_e32 v17, v81, v128
	v_sub_f32_e32 v16, v80, v128
	v_pk_mul_f32 v[16:17], v[128:129], v[16:17] op_sel:[1,0]
	v_pk_mul_f32 v[14:15], v[128:129], v[14:15] op_sel:[1,0]
	v_pk_fma_f32 v[18:19], v[16:17], v[4:5], v[8:9]
	v_pk_fma_f32 v[14:15], v[14:15], v[6:7], v[10:11]
	s_nop 0
	v_cndmask_b32_e32 v17, v162, v15, vcc
	v_cndmask_b32_e32 v16, v162, v14, vcc
	v_cndmask_b32_e32 v15, v162, v19, vcc
	v_cndmask_b32_e32 v14, v162, v18, vcc
	global_store_dwordx4 v[100:101], v[14:17], off offset:576 nt
	s_nop 1
	v_sub_f32_e32 v15, v51, v130
	v_sub_f32_e32 v14, v50, v130
	v_sub_f32_e32 v17, v49, v130
	v_sub_f32_e32 v16, v48, v130
	v_pk_mul_f32 v[16:17], v[130:131], v[16:17] op_sel:[1,0]
	v_pk_mul_f32 v[14:15], v[130:131], v[14:15] op_sel:[1,0]
	v_pk_fma_f32 v[18:19], v[16:17], v[4:5], v[8:9]
	v_pk_fma_f32 v[14:15], v[14:15], v[6:7], v[10:11]
	s_nop 0
	v_cndmask_b32_e32 v17, v162, v15, vcc
	v_cndmask_b32_e32 v16, v162, v14, vcc
	v_cndmask_b32_e32 v15, v162, v19, vcc
	v_cndmask_b32_e32 v14, v162, v18, vcc
	global_store_dwordx4 v[102:103], v[14:17], off offset:576 nt
	s_nop 1
	v_sub_f32_e32 v15, v23, v68
	v_sub_f32_e32 v14, v22, v68
	v_sub_f32_e32 v17, v21, v68
	v_sub_f32_e32 v16, v20, v68
	v_pk_mul_f32 v[16:17], v[68:69], v[16:17] op_sel:[1,0]
	v_pk_mul_f32 v[14:15], v[68:69], v[14:15] op_sel:[1,0]
	v_pk_fma_f32 v[18:19], v[16:17], v[4:5], v[8:9]
	v_pk_fma_f32 v[14:15], v[14:15], v[6:7], v[10:11]
	s_nop 0
	v_cndmask_b32_e32 v17, v162, v15, vcc
	v_cndmask_b32_e32 v16, v162, v14, vcc
	v_cndmask_b32_e32 v15, v162, v19, vcc
	v_cndmask_b32_e32 v14, v162, v18, vcc
	global_store_dwordx4 v[36:37], v[14:17], off offset:576 nt
